# nt hint also on the two input-conversion riders' loads and the out-proj epilogue's x loads, on top of the P0 nt version
# baseline (speedup 1.0000x reference)
;     __device__ __forceinline__ int lane_() const { return hw_lane(); }
; __device__ __forceinline__ void rider_convert(Frame& F, const Ptrs& P, int wu) {
;     int lane = F.lane_(); asm volatile("" : "+v"(lane));
;     const int r32 = lane & 31, hi = lane >> 5;
;     f32x4 pv[4];
; #pragma unroll
;     for (int j = 0; j < 4; ++j) pv[j] = *((const f32x4*)(P.p + (size_t)wu * 1024) + lane + 64 * j);
;     const bool has_w = wu < 3328;
;     const float* wsrc = nullptr; const float* wsc = nullptr; bf16* wdst = nullptr;
;     if (wu < 2048) { const int nb_ = wu & 31, k0 = (wu >> 5) * 32; wsrc = P.w_out + (size_t)k0 * DM + nb_ * 32; wdst = (bf16*)(P.ws + WS_WOUT) + (size_t)(nb_ * 32) * 2048 + k0; wsc = (k0 < 1024 ? P.ssd_nw + k0 : P.attn_nw + (k0 - 1024)); }
;     else if (wu < 3072) { const int r_ = wu - 2048, nb_ = r_ & 31, k0 = (r_ >> 5) * 32; wsrc = P.ple_gw + (size_t)k0 * DM + nb_ * 32; wdst = (bf16*)(P.ws + WS_WG) + (size_t)(nb_ * 32) * DM + k0; }
;     else if (wu < 3328) { const int r_ = wu - 3072, nb_ = r_ & 31, k0 = (r_ >> 5) * 32; wsrc = P.ple_proj + (size_t)k0 * DM + nb_ * 32; wdst = (bf16*)(P.ws + WS_WP) + (size_t)(nb_ * 32) * PLE + k0; }
;     const int wK = wu < 2048 ? 2048 : (wu < 3072 ? DM : PLE);
.LBB0_177:
	s_waitcnt lgkmcnt(0)
	s_barrier
	v_mbcnt_lo_u32_b32 v32, -1, 0
	v_mbcnt_hi_u32_b32 v32, -1, v32
	s_add_u32 s2, s18, s68
	s_addc_u32 s3, s19, s69
	v_ashrrev_i32_e32 v33, 31, v32
	v_lshl_add_u64 v[0:1], v[32:33], 4, s[2:3]
	global_load_dwordx4 v[12:15], v[0:1], off nt
	global_load_dwordx4 v[8:11], v[0:1], off offset:1024 nt
	global_load_dwordx4 v[4:7], v[0:1], off offset:2048 nt
	s_nop 0
	global_load_dwordx4 v[0:3], v[0:1], off offset:3072 nt
	s_cmpk_lt_i32 s70, 0xd00
	s_cselect_b64 s[10:11], -1, 0
	s_cmpk_lt_i32 s70, 0x800
	s_cselect_b64 s[6:7], -1, 0
	s_cmpk_gt_i32 s70, 0x7ff
	s_cbranch_scc0 .LBB0_181
	s_cmpk_gt_u32 s70, 0xbff
	s_cbranch_scc0 .LBB0_182
	s_mov_b64 s[2:3], 0
	s_andn2_b64 vcc, exec, s[10:11]
	s_mov_b64 s[16:17], 0
	s_mov_b64 s[8:9], 0
	s_cbranch_vccnz .LBB0_183
	s_and_b32 s8, s70, 0x7fffffe0
	s_addk_i32 s8, 0xf400
	s_mov_b32 s9, 0
	s_lshl_b64 s[12:13], s[8:9], 12
	s_add_u32 s12, s50, s12
	s_addc_u32 s13, s51, s13
	s_lshl_b32 s14, s70, 5
	s_and_b32 s14, s14, 0x3e0
	s_lshl_b32 s15, s14, 2
	s_add_u32 s16, s12, s15
	s_addc_u32 s17, s13, 0
	s_lshl_b32 s12, s14, 9
	s_add_u32 s12, s96, s12
	s_addc_u32 s13, s97, 0
	s_lshl_b64 s[8:9], s[8:9], 1
	s_add_u32 s8, s12, s8
	s_addc_u32 s9, s13, s9
	s_add_u32 s8, s8, 0x1300000
	s_addc_u32 s9, s9, 0
	s_branch .LBB0_183

; __device__ __forceinline__ void rider_convert(Frame& F, const Ptrs& P, int wu) {
;     ...
;     if (has_w) {
; #pragma unroll
;         for (int i = 0; i < 16; ++i) wv[i] = wsrc[(size_t)(hi * 16 + i) * DM + r32];
;         if (wsc) {
; #pragma unroll
;             for (int j = 0; j < 4; ++j) wsv[j] = *((const f32x4*)(wsc + hi * 16) + j); }
.LBB0_190:
	v_ashrrev_i32_e32 v16, 5, v32
	v_cndmask_b32_e64 v17, 0, 1, s[10:11]
	v_and_b32_e32 v36, 31, v32
	v_cmp_ne_u32_e64 s[2:3], 1, v17
	s_andn2_b64 vcc, exec, s[10:11]
	v_lshlrev_b32_e32 v34, 4, v16
	s_cbranch_vccnz .LBB0_193
	v_lshlrev_b32_e32 v16, 2, v36
	v_mov_b32_e32 v17, 0
	v_ashrrev_i32_e32 v35, 31, v34
	v_or_b32_e32 v20, 1, v34
	v_or_b32_e32 v22, 2, v34
	v_or_b32_e32 v24, 3, v34
	v_or_b32_e32 v26, 4, v34
	v_or_b32_e32 v28, 5, v34
	v_or_b32_e32 v30, 6, v34
	v_or_b32_e32 v38, 7, v34
	v_lshl_add_u64 v[16:17], s[16:17], 0, v[16:17]
	v_lshlrev_b64 v[18:19], 12, v[34:35]
	v_ashrrev_i32_e32 v21, 31, v20
	v_ashrrev_i32_e32 v23, 31, v22
	v_ashrrev_i32_e32 v25, 31, v24
	v_ashrrev_i32_e32 v27, 31, v26
	v_ashrrev_i32_e32 v29, 31, v28
	v_ashrrev_i32_e32 v31, 31, v30
	v_ashrrev_i32_e32 v39, 31, v38
	v_lshl_add_u64 v[18:19], v[16:17], 0, v[18:19]
	v_lshlrev_b64 v[20:21], 12, v[20:21]
	v_lshlrev_b64 v[22:23], 12, v[22:23]
	v_lshlrev_b64 v[24:25], 12, v[24:25]
	v_lshlrev_b64 v[26:27], 12, v[26:27]
	v_lshlrev_b64 v[28:29], 12, v[28:29]
	v_lshlrev_b64 v[30:31], 12, v[30:31]
	v_lshlrev_b64 v[38:39], 12, v[38:39]
	v_lshl_add_u64 v[20:21], v[16:17], 0, v[20:21]
	v_lshl_add_u64 v[22:23], v[16:17], 0, v[22:23]
	v_lshl_add_u64 v[24:25], v[16:17], 0, v[24:25]
	v_lshl_add_u64 v[26:27], v[16:17], 0, v[26:27]
	v_lshl_add_u64 v[28:29], v[16:17], 0, v[28:29]
	v_lshl_add_u64 v[30:31], v[16:17], 0, v[30:31]
	v_lshl_add_u64 v[46:47], v[16:17], 0, v[38:39]
	global_load_dword v38, v[18:19], off nt
	global_load_dword v39, v[20:21], off nt
	global_load_dword v40, v[22:23], off nt
	global_load_dword v41, v[24:25], off nt
	global_load_dword v42, v[26:27], off nt
	global_load_dword v43, v[28:29], off nt
	global_load_dword v44, v[30:31], off nt
	global_load_dword v45, v[46:47], off nt
	v_or_b32_e32 v18, 8, v34
	v_ashrrev_i32_e32 v19, 31, v18
	v_or_b32_e32 v20, 9, v34
	v_or_b32_e32 v22, 10, v34
	v_or_b32_e32 v24, 11, v34
	v_or_b32_e32 v26, 12, v34
	v_or_b32_e32 v28, 13, v34
	v_or_b32_e32 v30, 14, v34
	v_or_b32_e32 v46, 15, v34
	v_lshlrev_b64 v[18:19], 12, v[18:19]
	v_ashrrev_i32_e32 v21, 31, v20
	v_ashrrev_i32_e32 v23, 31, v22
	v_ashrrev_i32_e32 v25, 31, v24
	v_ashrrev_i32_e32 v27, 31, v26
	v_ashrrev_i32_e32 v29, 31, v28
	v_ashrrev_i32_e32 v31, 31, v30
	v_ashrrev_i32_e32 v47, 31, v46
	v_lshl_add_u64 v[18:19], v[16:17], 0, v[18:19]
	v_lshlrev_b64 v[20:21], 12, v[20:21]
	v_lshlrev_b64 v[22:23], 12, v[22:23]
	v_lshlrev_b64 v[24:25], 12, v[24:25]
	v_lshlrev_b64 v[26:27], 12, v[26:27]
	v_lshlrev_b64 v[28:29], 12, v[28:29]
	v_lshlrev_b64 v[30:31], 12, v[30:31]
	v_lshlrev_b64 v[46:47], 12, v[46:47]
	v_lshl_add_u64 v[20:21], v[16:17], 0, v[20:21]
	v_lshl_add_u64 v[22:23], v[16:17], 0, v[22:23]
	v_lshl_add_u64 v[24:25], v[16:17], 0, v[24:25]
	v_lshl_add_u64 v[26:27], v[16:17], 0, v[26:27]
	v_lshl_add_u64 v[28:29], v[16:17], 0, v[28:29]
	v_lshl_add_u64 v[30:31], v[16:17], 0, v[30:31]
	v_lshl_add_u64 v[16:17], v[16:17], 0, v[46:47]
	global_load_dword v46, v[18:19], off nt
	global_load_dword v47, v[20:21], off nt
	global_load_dword v48, v[22:23], off nt
	global_load_dword v49, v[24:25], off nt
	global_load_dword v50, v[26:27], off nt
	global_load_dword v51, v[28:29], off nt
	global_load_dword v52, v[30:31], off nt
	global_load_dword v53, v[16:17], off nt
	s_cmp_eq_u64 s[14:15], 0
	s_cbranch_scc1 .LBB0_194
	v_lshl_add_u64 v[28:29], v[34:35], 2, s[14:15]
	global_load_dwordx4 v[16:19], v[28:29], off nt
	global_load_dwordx4 v[20:23], v[28:29], off offset:16 nt
	global_load_dwordx4 v[24:27], v[28:29], off offset:32 nt
	s_nop 0
	global_load_dwordx4 v[28:31], v[28:29], off offset:48 nt
	s_branch .LBB0_195

; #define LAS __attribute__((address_space(3)))
;     __device__ __forceinline__ int lane_() const { return hw_lane(); }
; __device__ __forceinline__ void rider_convert(Frame& F, const Ptrs& P, int wu) {
;     int lane = F.lane_(); asm volatile("" : "+v"(lane));
;     const int r32 = lane & 31, hi = lane >> 5;
;     f32x4 pv[4];
; #pragma unroll
;     for (int j = 0; j < 4; ++j) pv[j] = *((const f32x4*)(P.p + (size_t)wu * 1024) + lane + 64 * j);
; __device__ __forceinline__ void attn_stage(Frame& F, const Ptrs& P, int u, bf16x8 (&qa)[4]) {
;     int lane = F.lane_(); asm volatile("" : "+v"(lane));
;     const int b = u >> 8, nb = u & 63, kvh = (u >> 6) & 3;
;     const int wid = F.wave, r32 = lane & 31, hi = lane >> 5;
;     LAS unsigned char* lds = F.lds;
;     const int hq = kvh * 4 + (wid >> 1), r0 = 64 * (wid & 1);
;     const size_t qrow = (size_t)b * SEQ + nb * 128 + r0;
;     const bf16* Qw = (const bf16*)(P.ws + WS_YG) + (qrow + r32) * 2048 + 1024 + hq * 64;
; #pragma unroll
;     for (int d0 = 0; d0 < 4; ++d0) qa[d0] = *(const bf16x8*)(Qw + d0 * 16 + hi * 8);
; #pragma unroll
;     for (int d0 = 0; d0 < 4; ++d0) __builtin_amdgcn_global_load_lds((const unsigned*)(Qw + (size_t)32 * 2048 + d0 * 16 + hi * 8), (LAS unsigned*)(lds + LDS_QB + wid * 4096 + d0 * 1024), 16, 0, 0);
;     const int t0 = nb * 128 - 128;
;     const bf16* Kh = (const bf16*)(P.ws + WS_K) + (size_t)b * SEQ * 256 + kvh * 64; const bf16* Vh = (const bf16*)(P.ws + WS_V) + (size_t)b * SEQ * 256 + kvh * 64;
; #pragma unroll
;     for (int j = 0; j < 6; ++j) {
;         int tk = t0 + j * 64 + lane; tk = tk < 0 ? 0 : (tk > SEQ - 1 ? SEQ - 1 : tk);
;         __builtin_amdgcn_global_load_lds((const unsigned*)(Kh + (size_t)tk * 256 + wid * 8), (LAS unsigned*)(lds + LDS_K + j * 8192 + wid * 1024), 16, 0, 0);
;         int tv = t0 + j * 64 + 16 * (wid & 3) + (lane >> 2); tv = tv < 0 ? 0 : (tv > SEQ - 1 ? SEQ - 1 : tv);
;         __builtin_amdgcn_global_load_lds((const unsigned*)(Vh + (size_t)tv * 256 + (wid >> 2) * 32 + (lane & 3) * 8), (LAS unsigned*)(lds + LDS_V + j * 8192 + wid * 1024), 16, 0, 0);
;     }
.LBB0_609:
	v_readlane_b32 s16, v252, 4
	s_ashr_i32 s2, s16, 8
	s_waitcnt lgkmcnt(0)
	s_barrier
	v_mbcnt_lo_u32_b32 v8, -1, 0
	v_mbcnt_hi_u32_b32 v8, -1, v8
	s_and_b32 s12, s28, 64
	s_ashr_i32 s3, s2, 31
	s_lshl_b32 s4, s16, 7
	s_bfe_u32 s6, s16, 0x20006
	s_and_b32 s7, s4, 0x1f80
	v_and_or_b32 v0, v8, 31, s12
	s_lshl_b64 s[4:5], s[2:3], 25
	v_or_b32_e32 v0, s7, v0
	s_add_u32 s4, s96, s4
	v_lshlrev_b32_e32 v0, 12, v0
	v_mov_b32_e32 v1, 0
	s_addc_u32 s5, s97, s5
	v_readlane_b32 s15, v252, 5
	v_lshl_add_u64 v[2:3], s[4:5], 0, v[0:1]
	s_lshl_b32 s5, s15, 5
	s_lshl_b32 s4, s6, 8
	s_and_b32 s13, s5, 0x7fffffc0
	s_add_i32 s4, s4, s13
	v_ashrrev_i32_e32 v0, 2, v8
	s_ashr_i32 s5, s4, 31
	v_and_b32_e32 v4, -8, v0
	v_lshl_add_u64 v[2:3], s[4:5], 1, v[2:3]
	v_ashrrev_i32_e32 v5, 31, v4
	v_lshl_add_u64 v[2:3], v[4:5], 1, v[2:3]
	s_mov_b64 s[4:5], 0x8c00800
	v_lshl_add_u64 v[4:5], v[2:3], 0, s[4:5]
	s_mov_b32 s4, 0x8c00000
	v_add_co_u32_e32 v6, vcc, s4, v2
	s_mov_b64 s[4:5], 0x8c20800
	s_nop 0
	v_addc_co_u32_e32 v7, vcc, 0, v3, vcc
	global_load_dwordx4 v[144:147], v[4:5], off offset:32 nt
	global_load_dwordx4 v[148:151], v[4:5], off offset:64 nt
	global_load_dwordx4 v[152:155], v[6:7], off offset:2048 nt
	global_load_dwordx4 v[156:159], v[4:5], off offset:96 nt
	v_lshl_add_u64 v[4:5], v[2:3], 0, s[4:5]
	s_lshl_b32 s4, s15, 12
	s_add_i32 s10, s4, 0
	s_add_i32 s30, s10, 0x18000
	s_mov_b32 m0, s30
	s_mov_b64 s[4:5], 0x8c20820
	global_load_lds_dwordx4 v[4:5], off
	v_lshl_add_u64 v[4:5], v[2:3], 0, s[4:5]
	s_add_i32 m0, s10, 0x18400
	s_mov_b64 s[4:5], 0x8c20840
	global_load_lds_dwordx4 v[4:5], off
	v_lshl_add_u64 v[4:5], v[2:3], 0, s[4:5]
	s_add_i32 m0, s10, 0x18800
	s_mov_b64 s[4:5], 0x8c20860
	global_load_lds_dwordx4 v[4:5], off
	s_add_i32 m0, s10, 0x18c00
	s_add_i32 s10, s7, 0xffffff80
	s_add_u32 s31, s96, 0xcc00000
	s_addc_u32 s33, s97, 0
	s_lshl_b64 s[2:3], s[2:3], 22
	v_lshl_add_u64 v[2:3], v[2:3], 0, s[4:5]
	s_add_u32 s4, s31, s2
	s_addc_u32 s5, s33, s3
	s_lshl_b32 s6, s6, 7
	s_add_u32 s4, s4, s6
	s_addc_u32 s5, s5, 0
	s_add_u32 s34, s96, 0xd400000
	s_addc_u32 s35, s97, 0
	s_add_u32 s2, s34, s2
	s_addc_u32 s3, s35, s3
	s_add_u32 s6, s2, s6
	s_addc_u32 s11, s3, 0
	s_lshl_b32 s28, s15, 3
	s_lshl_b32 s14, s15, 4
	s_add_u32 s2, s4, s14
	s_addc_u32 s3, s5, 0
	s_lshl_b32 s4, s15, 10
	s_add_i32 s61, s4, 0
	s_and_b32 s4, s28, 0x1fffffe0
	s_and_b32 s62, s14, 48
	s_lshl_b32 s63, s4, 1
	v_add_u32_e32 v6, s62, v0
	s_add_u32 s4, s6, s63
	v_lshlrev_b32_e32 v0, 4, v8
	s_addc_u32 s5, s11, 0
	v_and_b32_e32 v0, 48, v0
	global_load_lds_dwordx4 v[2:3], off
	v_lshl_add_u64 v[2:3], s[4:5], 0, v[0:1]
	v_add_u32_e32 v0, s10, v8
	v_mov_b32_e32 v7, 0x1fff
	v_med3_i32 v0, v0, 0, v7
	v_lshlrev_b32_e32 v0, 9, v0
	s_mov_b32 m0, s61
	s_sub_i32 s4, s7, 64
	global_load_lds_dwordx4 v0, s[2:3]
	v_add_u32_e32 v0, s10, v6
	v_med3_i32 v0, v0, 0, v7
	v_lshlrev_b32_e32 v0, 9, v0
	s_add_i32 s64, s61, 0xc000
	v_lshl_add_u64 v[4:5], v[2:3], 0, v[0:1]
	v_add_u32_e32 v0, s4, v8
	s_mov_b32 m0, s64
	v_med3_i32 v0, v0, 0, v7
	s_add_i32 s65, s61, 0x2000
	global_load_lds_dwordx4 v[4:5], off
	v_lshlrev_b32_e32 v0, 9, v0
	s_mov_b32 m0, s65
	s_add_i32 s68, s61, 0xe000
	global_load_lds_dwordx4 v0, s[2:3]
	v_add_u32_e32 v0, s4, v6
	v_med3_i32 v0, v0, 0, v7
	v_lshlrev_b32_e32 v0, 9, v0
	v_lshl_add_u64 v[4:5], v[2:3], 0, v[0:1]
	v_add_u32_e32 v0, s7, v8
	s_mov_b32 m0, s68
	v_med3_i32 v0, v0, 0, v7
	s_add_i32 s69, s61, 0x4000
	global_load_lds_dwordx4 v[4:5], off
	v_lshlrev_b32_e32 v0, 9, v0
	s_mov_b32 m0, s69
	s_or_b32 s4, s7, 64
	global_load_lds_dwordx4 v0, s[2:3]
	v_add_u32_e32 v0, s7, v6
	v_med3_i32 v0, v0, 0, v7
	v_lshlrev_b32_e32 v0, 9, v0
	v_lshl_add_u64 v[4:5], v[2:3], 0, v[0:1]
	v_add_u32_e32 v0, s4, v8
	s_add_i32 m0, s61, 0x10000
	v_med3_i32 v0, v0, 0, v7
	s_add_i32 s70, s61, 0x6000
	global_load_lds_dwordx4 v[4:5], off
	v_lshlrev_b32_e32 v0, 9, v0
	s_mov_b32 m0, s70
	s_add_i32 s71, s61, 0x8000
	global_load_lds_dwordx4 v0, s[2:3]
	v_add_u32_e32 v0, s4, v6
	v_med3_i32 v0, v0, 0, v7
	v_lshlrev_b32_e32 v0, 9, v0
	s_add_i32 s4, s7, 0x80
	v_lshl_add_u64 v[4:5], v[2:3], 0, v[0:1]
	v_add_u32_e32 v0, s4, v8
	s_add_i32 m0, s61, 0x12000
	v_med3_i32 v0, v0, 0, v7
	global_load_lds_dwordx4 v[4:5], off
	v_lshlrev_b32_e32 v0, 9, v0
	s_mov_b32 m0, s71
	s_addk_i32 s7, 0xc0
	global_load_lds_dwordx4 v0, s[2:3]
	v_add_u32_e32 v0, s4, v6
	v_med3_i32 v0, v0, 0, v7
	v_lshlrev_b32_e32 v0, 9, v0
	v_lshl_add_u64 v[4:5], v[2:3], 0, v[0:1]
	v_add_u32_e32 v0, s7, v8
	s_add_i32 m0, s61, 0x14000
	v_med3_i32 v0, v0, 0, v7
	s_add_i32 s72, s61, 0xa000
	global_load_lds_dwordx4 v[4:5], off
	v_lshlrev_b32_e32 v0, 9, v0
	s_mov_b32 m0, s72
	s_nop 0
	global_load_lds_dwordx4 v0, s[2:3]
	s_lshl_b32 s2, s16, 3
	v_add_u32_e32 v0, s7, v6
	s_add_i32 s2, s15, s2
	v_med3_i32 v0, v0, 0, v7
	s_add_i32 s4, s2, 0x800
	v_lshlrev_b32_e32 v0, 9, v0
	s_ashr_i32 s5, s4, 31
	v_lshl_add_u64 v[0:1], v[2:3], 0, v[0:1]
	s_add_i32 m0, s61, 0x16000
	s_lshl_b64 s[2:3], s[4:5], 12
	global_load_lds_dwordx4 v[0:1], off
	v_mbcnt_lo_u32_b32 v32, -1, 0
	v_mbcnt_hi_u32_b32 v32, -1, v32
	s_add_u32 s2, s18, s2
	s_addc_u32 s3, s19, s3
	v_ashrrev_i32_e32 v33, 31, v32
	v_lshl_add_u64 v[0:1], v[32:33], 4, s[2:3]
	global_load_dwordx4 v[12:15], v[0:1], off nt
	global_load_dwordx4 v[8:11], v[0:1], off offset:1024 nt
	global_load_dwordx4 v[4:7], v[0:1], off offset:2048 nt
	s_nop 0
	global_load_dwordx4 v[0:3], v[0:1], off offset:3072 nt
	s_cmpk_lt_i32 s4, 0xd00
	s_cselect_b64 s[14:15], -1, 0
	s_cmpk_lt_i32 s4, 0x800
	s_cselect_b64 s[6:7], -1, 0
	s_cmpk_gt_i32 s4, 0x7ff
	s_cbranch_scc0 .LBB0_613
	s_cmpk_gt_u32 s4, 0xbff
	s_cbranch_scc0 .LBB0_614
	s_mov_b64 s[2:3], 0
	s_andn2_b64 vcc, exec, s[14:15]
	s_mov_b64 s[18:19], 0
	s_mov_b64 s[10:11], 0
	s_cbranch_vccnz .LBB0_615
	s_and_b32 s10, s4, 0x7fffffe0
	s_addk_i32 s10, 0xf400
	s_mov_b32 s11, 0
	s_lshl_b64 s[16:17], s[10:11], 12
	s_add_u32 s16, s50, s16
	s_addc_u32 s17, s51, s17
	s_lshl_b32 s18, s4, 5
	s_and_b32 s20, s18, 0x3e0
	s_lshl_b32 s18, s20, 2
	s_add_u32 s18, s16, s18
	s_addc_u32 s19, s17, 0
	s_lshl_b32 s16, s20, 9
	s_add_u32 s16, s96, s16
	s_addc_u32 s17, s97, 0
	s_lshl_b64 s[10:11], s[10:11], 1
	s_add_u32 s10, s16, s10
	s_addc_u32 s11, s17, s11
	s_add_u32 s10, s10, 0x1300000
	s_addc_u32 s11, s11, 0
	s_branch .LBB0_615

; __device__ __forceinline__ void rider_convert(Frame& F, const Ptrs& P, int wu) {
;     ...
;     if (has_w) {
; #pragma unroll
;         for (int i = 0; i < 16; ++i) wv[i] = wsrc[(size_t)(hi * 16 + i) * DM + r32];
;         if (wsc) {
; #pragma unroll
;             for (int j = 0; j < 4; ++j) wsv[j] = *((const f32x4*)(wsc + hi * 16) + j); }
.LBB0_622:
	v_ashrrev_i32_e32 v16, 5, v32
	v_cndmask_b32_e64 v17, 0, 1, s[14:15]
	v_and_b32_e32 v36, 31, v32
	v_cmp_ne_u32_e64 s[2:3], 1, v17
	s_andn2_b64 vcc, exec, s[14:15]
	v_lshlrev_b32_e32 v34, 4, v16
	s_cbranch_vccnz .LBB0_625
	v_lshlrev_b32_e32 v16, 2, v36
	v_mov_b32_e32 v17, 0
	v_ashrrev_i32_e32 v35, 31, v34
	v_or_b32_e32 v20, 1, v34
	v_or_b32_e32 v22, 2, v34
	v_or_b32_e32 v24, 3, v34
	v_or_b32_e32 v26, 4, v34
	v_or_b32_e32 v28, 5, v34
	v_or_b32_e32 v30, 6, v34
	v_or_b32_e32 v38, 7, v34
	v_lshl_add_u64 v[16:17], s[18:19], 0, v[16:17]
	v_lshlrev_b64 v[18:19], 12, v[34:35]
	v_ashrrev_i32_e32 v21, 31, v20
	v_ashrrev_i32_e32 v23, 31, v22
	v_ashrrev_i32_e32 v25, 31, v24
	v_ashrrev_i32_e32 v27, 31, v26
	v_ashrrev_i32_e32 v29, 31, v28
	v_ashrrev_i32_e32 v31, 31, v30
	v_ashrrev_i32_e32 v39, 31, v38
	v_lshl_add_u64 v[18:19], v[16:17], 0, v[18:19]
	v_lshlrev_b64 v[20:21], 12, v[20:21]
	v_lshlrev_b64 v[22:23], 12, v[22:23]
	v_lshlrev_b64 v[24:25], 12, v[24:25]
	v_lshlrev_b64 v[26:27], 12, v[26:27]
	v_lshlrev_b64 v[28:29], 12, v[28:29]
	v_lshlrev_b64 v[30:31], 12, v[30:31]
	v_lshlrev_b64 v[38:39], 12, v[38:39]
	v_lshl_add_u64 v[20:21], v[16:17], 0, v[20:21]
	v_lshl_add_u64 v[22:23], v[16:17], 0, v[22:23]
	v_lshl_add_u64 v[24:25], v[16:17], 0, v[24:25]
	v_lshl_add_u64 v[26:27], v[16:17], 0, v[26:27]
	v_lshl_add_u64 v[28:29], v[16:17], 0, v[28:29]
	v_lshl_add_u64 v[30:31], v[16:17], 0, v[30:31]
	v_lshl_add_u64 v[46:47], v[16:17], 0, v[38:39]
	global_load_dword v38, v[18:19], off nt
	global_load_dword v39, v[20:21], off nt
	global_load_dword v40, v[22:23], off nt
	global_load_dword v41, v[24:25], off nt
	global_load_dword v42, v[26:27], off nt
	global_load_dword v43, v[28:29], off nt
	global_load_dword v44, v[30:31], off nt
	global_load_dword v45, v[46:47], off nt
	v_or_b32_e32 v18, 8, v34
	v_ashrrev_i32_e32 v19, 31, v18
	v_or_b32_e32 v20, 9, v34
	v_or_b32_e32 v22, 10, v34
	v_or_b32_e32 v24, 11, v34
	v_or_b32_e32 v26, 12, v34
	v_or_b32_e32 v28, 13, v34
	v_or_b32_e32 v30, 14, v34
	v_or_b32_e32 v46, 15, v34
	v_lshlrev_b64 v[18:19], 12, v[18:19]
	v_ashrrev_i32_e32 v21, 31, v20
	v_ashrrev_i32_e32 v23, 31, v22
	v_ashrrev_i32_e32 v25, 31, v24
	v_ashrrev_i32_e32 v27, 31, v26
	v_ashrrev_i32_e32 v29, 31, v28
	v_ashrrev_i32_e32 v31, 31, v30
	v_ashrrev_i32_e32 v47, 31, v46
	v_lshl_add_u64 v[18:19], v[16:17], 0, v[18:19]
	v_lshlrev_b64 v[20:21], 12, v[20:21]
	v_lshlrev_b64 v[22:23], 12, v[22:23]
	v_lshlrev_b64 v[24:25], 12, v[24:25]
	v_lshlrev_b64 v[26:27], 12, v[26:27]
	v_lshlrev_b64 v[28:29], 12, v[28:29]
	v_lshlrev_b64 v[30:31], 12, v[30:31]
	v_lshlrev_b64 v[46:47], 12, v[46:47]
	v_lshl_add_u64 v[20:21], v[16:17], 0, v[20:21]
	v_lshl_add_u64 v[22:23], v[16:17], 0, v[22:23]
	v_lshl_add_u64 v[24:25], v[16:17], 0, v[24:25]
	v_lshl_add_u64 v[26:27], v[16:17], 0, v[26:27]
	v_lshl_add_u64 v[28:29], v[16:17], 0, v[28:29]
	v_lshl_add_u64 v[30:31], v[16:17], 0, v[30:31]
	v_lshl_add_u64 v[16:17], v[16:17], 0, v[46:47]
	global_load_dword v46, v[18:19], off nt
	global_load_dword v47, v[20:21], off nt
	global_load_dword v48, v[22:23], off nt
	global_load_dword v49, v[24:25], off nt
	global_load_dword v50, v[26:27], off nt
	global_load_dword v51, v[28:29], off nt
	global_load_dword v52, v[30:31], off nt
	global_load_dword v53, v[16:17], off nt
	s_cmp_eq_u64 s[16:17], 0
	s_cbranch_scc1 .LBB0_626
	v_lshl_add_u64 v[28:29], v[34:35], 2, s[16:17]
	global_load_dwordx4 v[16:19], v[28:29], off nt
	global_load_dwordx4 v[20:23], v[28:29], off offset:16 nt
	global_load_dwordx4 v[24:27], v[28:29], off offset:32 nt
	s_nop 0
	global_load_dwordx4 v[28:31], v[28:29], off offset:48 nt
	s_branch .LBB0_627

; __device__ __forceinline__ unsigned cvt_pk_bf16(float lo, float hi) { unsigned r; asm volatile("v_cvt_pk_bf16_f32 %0, %1, %2" : "=v"(r) : "v"(lo), "v"(hi)); return r; }
;     __device__ __forceinline__ void operator()(const f32x4 (&acc)[2][2][4][2], const Unit& u, int wr, int wc, int fr, int fq) const {
;         const int col0 = u.pn * BM + wc * 32 + 8 * fq;
; #pragma unroll
;         for (int ai = 0; ai < 2; ++ai)
; #pragma unroll
;             for (int m = 0; m < 4; ++m) { const int rt = ai * HALF + wr * 64 + m * 16 + fr; const float r = tab[256 + rt]; const size_t off = (size_t)(u.pm * BM + rt) * 1024 + col0;
; #pragma unroll
;                 for (int bj = 0; bj < 2; ++bj) {
;                     const u32x4 xw = *(const u32x4*)(x1b + off + bj * HALF);
;                     f32x4 x0, x1;
;                     x0[0] = __uint_as_float(xw.x << 16); x0[1] = __uint_as_float(xw.x & 0xffff0000u); x0[2] = __uint_as_float(xw.y << 16); x0[3] = __uint_as_float(xw.y & 0xffff0000u);
;                     x1[0] = __uint_as_float(xw.z << 16); x1[1] = __uint_as_float(xw.z & 0xffff0000u); x1[2] = __uint_as_float(xw.w << 16); x1[3] = __uint_as_float(xw.w & 0xffff0000u);
;                     const f32x4 v0 = x0 + acc[ai][bj][m][0] * r, v1 = x1 + acc[ai][bj][m][1] * r;
;                     u32x4 w; w.x = cvt_pk_bf16(v0[0], v0[1]); w.y = cvt_pk_bf16(v0[2], v0[3]); w.z = cvt_pk_bf16(v1[0], v1[1]); w.w = cvt_pk_bf16(v1[2], v1[3]);
;                     *(u32x4*)(x1b + off + bj * HALF) = w; } }
.LBB0_879:
	s_add_u32 s24, s96, 0x1400000
	s_addc_u32 s25, s97, 0
	v_ashrrev_i32_e32 v128, 1, v143
	s_lshl_b32 s8, s8, 8
	v_and_b32_e32 v128, -8, v128
	s_or_b32 s8, s8, s52
	v_add_u32_e32 v130, s6, v142
	v_add_u32_e32 v128, s8, v128
	v_ashrrev_i32_e32 v131, 31, v130
	v_ashrrev_i32_e32 v129, 31, v128
	v_lshlrev_b64 v[132:133], 11, v[130:131]
	v_lshl_add_u64 v[132:133], s[24:25], 0, v[132:133]
	v_lshlrev_b64 v[128:129], 1, v[128:129]
	v_lshl_add_u64 v[144:145], v[132:133], 0, v[128:129]
	s_mov_b32 s99, 0
	global_load_dwordx4 v[152:155], v[144:145], off nt
	global_load_dwordx4 v[156:159], v[144:145], off offset:256 nt
	s_mov_b32 s98, 0x8000
	v_lshl_add_u64 v[216:217], v[144:145], 0, s[98:99]
	global_load_dwordx4 v[160:163], v[216:217], off nt
	global_load_dwordx4 v[164:167], v[216:217], off offset:256 nt
	s_mov_b32 s98, 0x10000
	v_lshl_add_u64 v[216:217], v[144:145], 0, s[98:99]
	global_load_dwordx4 v[168:171], v[216:217], off nt
	global_load_dwordx4 v[172:175], v[216:217], off offset:256 nt
	s_mov_b32 s98, 0x18000
	v_lshl_add_u64 v[216:217], v[144:145], 0, s[98:99]
	global_load_dwordx4 v[176:179], v[216:217], off nt
	global_load_dwordx4 v[180:183], v[216:217], off offset:256 nt
	s_mov_b32 s98, 0x40000
	v_lshl_add_u64 v[216:217], v[144:145], 0, s[98:99]
	global_load_dwordx4 v[184:187], v[216:217], off nt
	global_load_dwordx4 v[188:191], v[216:217], off offset:256 nt
	s_mov_b32 s98, 0x48000
	v_lshl_add_u64 v[216:217], v[144:145], 0, s[98:99]
	global_load_dwordx4 v[192:195], v[216:217], off nt
	global_load_dwordx4 v[196:199], v[216:217], off offset:256 nt
	s_mov_b32 s98, 0x50000
	v_lshl_add_u64 v[216:217], v[144:145], 0, s[98:99]
	global_load_dwordx4 v[200:203], v[216:217], off nt
	global_load_dwordx4 v[204:207], v[216:217], off offset:256 nt
	s_mov_b32 s98, 0x58000
	v_lshl_add_u64 v[216:217], v[144:145], 0, s[98:99]
	global_load_dwordx4 v[208:211], v[216:217], off nt
	global_load_dwordx4 v[212:215], v[216:217], off offset:256 nt
	s_waitcnt vmcnt(15)
	v_mov_b32_e32 v132, v152
	v_mov_b32_e32 v133, v153
	v_mov_b32_e32 v134, v154
	v_mov_b32_e32 v135, v155
	v_lshl_add_u32 v131, v142, 2, s7
	ds_read_b32 v146, v131 offset:1024
	v_readlane_b32 s8, v252, 11
	v_readlane_b32 s9, v252, 12
	s_andn2_b64 vcc, exec, s[8:9]
	s_nop 0
	v_lshlrev_b32_e32 v148, 16, v132
	v_and_b32_e32 v149, 0xffff0000, v132
	v_lshlrev_b32_e32 v132, 16, v133
	v_and_b32_e32 v133, 0xffff0000, v133
	v_lshlrev_b32_e32 v150, 16, v134
	v_and_b32_e32 v151, 0xffff0000, v134
	v_lshlrev_b32_e32 v134, 16, v135
	v_and_b32_e32 v135, 0xffff0000, v135
	s_waitcnt lgkmcnt(0)
	v_pk_fma_f32 v[126:127], v[126:127], v[146:147], v[132:133] op_sel_hi:[1,0,1]
	v_pk_fma_f32 v[124:125], v[124:125], v[146:147], v[148:149] op_sel_hi:[1,0,1]
	v_pk_fma_f32 v[132:133], v[122:123], v[146:147], v[134:135] op_sel_hi:[1,0,1]
	v_pk_fma_f32 v[122:123], v[120:121], v[146:147], v[150:151] op_sel_hi:[1,0,1]
	v_cvt_pk_bf16_f32 v120, v124, v125
	v_cvt_pk_bf16_f32 v121, v126, v127
	v_or_b32_e32 v134, 16, v142
	v_cvt_pk_bf16_f32 v122, v122, v123
	v_cvt_pk_bf16_f32 v123, v132, v133
	s_waitcnt vmcnt(14)
	v_mov_b32_e32 v124, v156
	v_mov_b32_e32 v125, v157
	v_mov_b32_e32 v126, v158
	v_mov_b32_e32 v127, v159
	v_add_u32_e32 v132, s6, v134
	v_ashrrev_i32_e32 v133, 31, v132
	v_lshlrev_b64 v[132:133], 11, v[132:133]
	v_lshl_add_u64 v[132:133], s[24:25], 0, v[132:133]
	global_store_dwordx4 v[144:145], v[120:123], off
	v_lshl_add_u64 v[132:133], v[132:133], 0, v[128:129]
	s_nop 0
	v_lshlrev_b32_e32 v120, 16, v124
	v_and_b32_e32 v121, 0xffff0000, v124
	v_lshlrev_b32_e32 v122, 16, v125
	v_and_b32_e32 v123, 0xffff0000, v125
	v_lshlrev_b32_e32 v124, 16, v126
	v_and_b32_e32 v125, 0xffff0000, v126
	v_lshlrev_b32_e32 v126, 16, v127
	v_and_b32_e32 v127, 0xffff0000, v127
	v_pk_fma_f32 v[114:115], v[114:115], v[146:147], v[122:123] op_sel_hi:[1,0,1]
	v_pk_fma_f32 v[112:113], v[112:113], v[146:147], v[120:121] op_sel_hi:[1,0,1]
	v_pk_fma_f32 v[118:119], v[118:119], v[146:147], v[126:127] op_sel_hi:[1,0,1]
	v_pk_fma_f32 v[116:117], v[116:117], v[146:147], v[124:125] op_sel_hi:[1,0,1]
	v_cvt_pk_bf16_f32 v112, v112, v113
	v_cvt_pk_bf16_f32 v113, v114, v115
	v_lshl_add_u32 v120, v134, 2, s7
	v_cvt_pk_bf16_f32 v114, v116, v117
	v_cvt_pk_bf16_f32 v115, v118, v119
	s_waitcnt vmcnt(14)
	v_mov_b32_e32 v116, v160
	v_mov_b32_e32 v117, v161
	v_mov_b32_e32 v118, v162
	v_mov_b32_e32 v119, v163
	ds_read_b32 v120, v120 offset:1024
	global_store_dwordx4 v[144:145], v[112:115], off offset:256
	s_nop 0
	s_nop 0
	v_lshlrev_b32_e32 v112, 16, v116
	v_and_b32_e32 v113, 0xffff0000, v116
	v_lshlrev_b32_e32 v114, 16, v117
	v_and_b32_e32 v115, 0xffff0000, v117
	v_lshlrev_b32_e32 v116, 16, v118
	v_and_b32_e32 v117, 0xffff0000, v118
	v_lshlrev_b32_e32 v118, 16, v119
	v_and_b32_e32 v119, 0xffff0000, v119
	s_waitcnt lgkmcnt(0)
	v_pk_fma_f32 v[110:111], v[110:111], v[120:121], v[114:115] op_sel_hi:[1,0,1]
	v_pk_fma_f32 v[108:109], v[108:109], v[120:121], v[112:113] op_sel_hi:[1,0,1]
	v_pk_fma_f32 v[112:113], v[106:107], v[120:121], v[118:119] op_sel_hi:[1,0,1]
	v_pk_fma_f32 v[106:107], v[104:105], v[120:121], v[116:117] op_sel_hi:[1,0,1]
	v_cvt_pk_bf16_f32 v104, v108, v109
	v_cvt_pk_bf16_f32 v105, v110, v111
	v_or_b32_e32 v114, 32, v142
	v_cvt_pk_bf16_f32 v106, v106, v107
	v_cvt_pk_bf16_f32 v107, v112, v113
	s_waitcnt vmcnt(14)
; __device__ __forceinline__ unsigned cvt_pk_bf16(float lo, float hi) { unsigned r; asm volatile("v_cvt_pk_bf16_f32 %0, %1, %2" : "=v"(r) : "v"(lo), "v"(hi)); return r; }
;     __device__ __forceinline__ void operator()(const f32x4 (&acc)[2][2][4][2], const Unit& u, int wr, int wc, int fr, int fq) const {
;     ...
;             for (int m = 0; m < 4; ++m) { const int rt = ai * HALF + wr * 64 + m * 16 + fr; const float r = tab[256 + rt]; const size_t off = (size_t)(u.pm * BM + rt) * 1024 + col0;
; #pragma unroll
;                 for (int bj = 0; bj < 2; ++bj) {
;                     const u32x4 xw = *(const u32x4*)(x1b + off + bj * HALF);
;                     f32x4 x0, x1;
;                     x0[0] = __uint_as_float(xw.x << 16); x0[1] = __uint_as_float(xw.x & 0xffff0000u); x0[2] = __uint_as_float(xw.y << 16); x0[3] = __uint_as_float(xw.y & 0xffff0000u);
;                     x1[0] = __uint_as_float(xw.z << 16); x1[1] = __uint_as_float(xw.z & 0xffff0000u); x1[2] = __uint_as_float(xw.w << 16); x1[3] = __uint_as_float(xw.w & 0xffff0000u);
;                     const f32x4 v0 = x0 + acc[ai][bj][m][0] * r, v1 = x1 + acc[ai][bj][m][1] * r;
;                     u32x4 w; w.x = cvt_pk_bf16(v0[0], v0[1]); w.y = cvt_pk_bf16(v0[2], v0[3]); w.z = cvt_pk_bf16(v1[0], v1[1]); w.w = cvt_pk_bf16(v1[2], v1[3]);
;                     *(u32x4*)(x1b + off + bj * HALF) = w; } }
	v_mov_b32_e32 v108, v164
	v_mov_b32_e32 v109, v165
	v_mov_b32_e32 v110, v166
	v_mov_b32_e32 v111, v167
	v_add_u32_e32 v112, s6, v114
	v_ashrrev_i32_e32 v113, 31, v112
	v_lshlrev_b64 v[112:113], 11, v[112:113]
	v_lshl_add_u64 v[112:113], s[24:25], 0, v[112:113]
	global_store_dwordx4 v[132:133], v[104:107], off
	v_lshl_add_u64 v[112:113], v[112:113], 0, v[128:129]
	s_nop 0
	v_lshlrev_b32_e32 v104, 16, v108
	v_and_b32_e32 v105, 0xffff0000, v108
	v_lshlrev_b32_e32 v106, 16, v109
	v_and_b32_e32 v107, 0xffff0000, v109
	v_lshlrev_b32_e32 v108, 16, v110
	v_and_b32_e32 v109, 0xffff0000, v110
	v_lshlrev_b32_e32 v110, 16, v111
	v_and_b32_e32 v111, 0xffff0000, v111
	v_pk_fma_f32 v[98:99], v[98:99], v[120:121], v[106:107] op_sel_hi:[1,0,1]
	v_pk_fma_f32 v[96:97], v[96:97], v[120:121], v[104:105] op_sel_hi:[1,0,1]
	v_pk_fma_f32 v[102:103], v[102:103], v[120:121], v[110:111] op_sel_hi:[1,0,1]
	v_pk_fma_f32 v[100:101], v[100:101], v[120:121], v[108:109] op_sel_hi:[1,0,1]
	v_cvt_pk_bf16_f32 v96, v96, v97
	v_cvt_pk_bf16_f32 v97, v98, v99
	v_lshl_add_u32 v104, v114, 2, s7
	v_cvt_pk_bf16_f32 v98, v100, v101
	v_cvt_pk_bf16_f32 v99, v102, v103
	s_waitcnt vmcnt(14)
	v_mov_b32_e32 v100, v168
	v_mov_b32_e32 v101, v169
	v_mov_b32_e32 v102, v170
	v_mov_b32_e32 v103, v171
	ds_read_b32 v104, v104 offset:1024
	global_store_dwordx4 v[132:133], v[96:99], off offset:256
	s_nop 0
	s_nop 0
	v_lshlrev_b32_e32 v96, 16, v100
	v_and_b32_e32 v97, 0xffff0000, v100
	v_lshlrev_b32_e32 v98, 16, v101
	v_and_b32_e32 v99, 0xffff0000, v101
	v_lshlrev_b32_e32 v100, 16, v102
	v_and_b32_e32 v101, 0xffff0000, v102
	v_lshlrev_b32_e32 v102, 16, v103
	v_and_b32_e32 v103, 0xffff0000, v103
	s_waitcnt lgkmcnt(0)
	v_pk_fma_f32 v[94:95], v[94:95], v[104:105], v[98:99] op_sel_hi:[1,0,1]
	v_pk_fma_f32 v[92:93], v[92:93], v[104:105], v[96:97] op_sel_hi:[1,0,1]
	v_pk_fma_f32 v[96:97], v[90:91], v[104:105], v[102:103] op_sel_hi:[1,0,1]
	v_pk_fma_f32 v[90:91], v[88:89], v[104:105], v[100:101] op_sel_hi:[1,0,1]
	v_cvt_pk_bf16_f32 v88, v92, v93
	v_cvt_pk_bf16_f32 v89, v94, v95
	v_or_b32_e32 v98, 48, v142
	v_cvt_pk_bf16_f32 v90, v90, v91
	v_cvt_pk_bf16_f32 v91, v96, v97
	s_waitcnt vmcnt(14)
	v_mov_b32_e32 v92, v172
	v_mov_b32_e32 v93, v173
	v_mov_b32_e32 v94, v174
	v_mov_b32_e32 v95, v175
	v_add_u32_e32 v96, s6, v98
	v_ashrrev_i32_e32 v97, 31, v96
	v_lshlrev_b64 v[96:97], 11, v[96:97]
	v_lshl_add_u64 v[96:97], s[24:25], 0, v[96:97]
	global_store_dwordx4 v[112:113], v[88:91], off
	v_lshl_add_u64 v[96:97], v[96:97], 0, v[128:129]
	s_nop 0
	v_lshlrev_b32_e32 v88, 16, v92
	v_and_b32_e32 v89, 0xffff0000, v92
	v_lshlrev_b32_e32 v90, 16, v93
	v_and_b32_e32 v91, 0xffff0000, v93
	v_lshlrev_b32_e32 v92, 16, v94
	v_and_b32_e32 v93, 0xffff0000, v94
	v_lshlrev_b32_e32 v94, 16, v95
	v_and_b32_e32 v95, 0xffff0000, v95
	v_pk_fma_f32 v[82:83], v[82:83], v[104:105], v[90:91] op_sel_hi:[1,0,1]
	v_pk_fma_f32 v[80:81], v[80:81], v[104:105], v[88:89] op_sel_hi:[1,0,1]
	v_pk_fma_f32 v[86:87], v[86:87], v[104:105], v[94:95] op_sel_hi:[1,0,1]
	v_pk_fma_f32 v[84:85], v[84:85], v[104:105], v[92:93] op_sel_hi:[1,0,1]
	v_cvt_pk_bf16_f32 v80, v80, v81
	v_cvt_pk_bf16_f32 v81, v82, v83
	v_lshl_add_u32 v88, v98, 2, s7
	v_cvt_pk_bf16_f32 v82, v84, v85
	v_cvt_pk_bf16_f32 v83, v86, v87
	s_waitcnt vmcnt(14)
	v_mov_b32_e32 v84, v176
	v_mov_b32_e32 v85, v177
	v_mov_b32_e32 v86, v178
	v_mov_b32_e32 v87, v179
	ds_read_b32 v88, v88 offset:1024
	global_store_dwordx4 v[112:113], v[80:83], off offset:256
	s_nop 0
	s_nop 0
	v_lshlrev_b32_e32 v80, 16, v84
	v_and_b32_e32 v81, 0xffff0000, v84
	v_lshlrev_b32_e32 v82, 16, v85
	v_and_b32_e32 v83, 0xffff0000, v85
	v_lshlrev_b32_e32 v84, 16, v86
	v_and_b32_e32 v85, 0xffff0000, v86
	v_lshlrev_b32_e32 v86, 16, v87
	v_and_b32_e32 v87, 0xffff0000, v87
	s_waitcnt lgkmcnt(0)
	v_pk_fma_f32 v[78:79], v[78:79], v[88:89], v[82:83] op_sel_hi:[1,0,1]
	v_pk_fma_f32 v[76:77], v[76:77], v[88:89], v[80:81] op_sel_hi:[1,0,1]
	v_pk_fma_f32 v[80:81], v[74:75], v[88:89], v[86:87] op_sel_hi:[1,0,1]
	v_pk_fma_f32 v[74:75], v[72:73], v[88:89], v[84:85] op_sel_hi:[1,0,1]
	v_cvt_pk_bf16_f32 v72, v76, v77
	v_cvt_pk_bf16_f32 v73, v78, v79
	s_nop 0
	v_cvt_pk_bf16_f32 v74, v74, v75
	v_cvt_pk_bf16_f32 v75, v80, v81
	s_waitcnt vmcnt(14)
	v_mov_b32_e32 v76, v180
	v_mov_b32_e32 v77, v181
	v_mov_b32_e32 v78, v182
	v_mov_b32_e32 v79, v183
	v_add_u32_e32 v80, 0x80, v130
	v_ashrrev_i32_e32 v81, 31, v80
	v_lshlrev_b64 v[80:81], 11, v[80:81]
	v_lshl_add_u64 v[80:81], s[24:25], 0, v[80:81]
	global_store_dwordx4 v[96:97], v[72:75], off
	v_lshl_add_u64 v[80:81], v[80:81], 0, v[128:129]
	s_nop 0
	v_lshlrev_b32_e32 v72, 16, v76
	v_and_b32_e32 v73, 0xffff0000, v76
	v_lshlrev_b32_e32 v74, 16, v77
	v_and_b32_e32 v75, 0xffff0000, v77
	v_lshlrev_b32_e32 v76, 16, v78
	v_and_b32_e32 v77, 0xffff0000, v78
	v_lshlrev_b32_e32 v78, 16, v79
	v_and_b32_e32 v79, 0xffff0000, v79
	v_pk_fma_f32 v[58:59], v[58:59], v[88:89], v[74:75] op_sel_hi:[1,0,1]
	v_pk_fma_f32 v[56:57], v[56:57], v[88:89], v[72:73] op_sel_hi:[1,0,1]
	v_pk_fma_f32 v[62:63], v[62:63], v[88:89], v[78:79] op_sel_hi:[1,0,1]
	v_pk_fma_f32 v[60:61], v[60:61], v[88:89], v[76:77] op_sel_hi:[1,0,1]
	v_cvt_pk_bf16_f32 v56, v56, v57
	v_cvt_pk_bf16_f32 v57, v58, v59
	s_nop 0
	v_cvt_pk_bf16_f32 v58, v60, v61
	v_cvt_pk_bf16_f32 v59, v62, v63
	s_waitcnt vmcnt(14)
	v_mov_b32_e32 v60, v184
	v_mov_b32_e32 v61, v185
	v_mov_b32_e32 v62, v186
	v_mov_b32_e32 v63, v187
	ds_read_b32 v72, v131 offset:1536
	global_store_dwordx4 v[96:97], v[56:59], off offset:256
	s_nop 0
	s_nop 0
	v_lshlrev_b32_e32 v56, 16, v60
	v_and_b32_e32 v57, 0xffff0000, v60
	v_lshlrev_b32_e32 v58, 16, v61
	v_and_b32_e32 v59, 0xffff0000, v61
	v_lshlrev_b32_e32 v60, 16, v62
	v_and_b32_e32 v61, 0xffff0000, v62
	v_lshlrev_b32_e32 v62, 16, v63
	v_and_b32_e32 v63, 0xffff0000, v63
	s_waitcnt lgkmcnt(0)
; __device__ __forceinline__ unsigned cvt_pk_bf16(float lo, float hi) { unsigned r; asm volatile("v_cvt_pk_bf16_f32 %0, %1, %2" : "=v"(r) : "v"(lo), "v"(hi)); return r; }
;     __device__ __forceinline__ void operator()(const f32x4 (&acc)[2][2][4][2], const Unit& u, int wr, int wc, int fr, int fq) const {
;     ...
;             for (int m = 0; m < 4; ++m) { const int rt = ai * HALF + wr * 64 + m * 16 + fr; const float r = tab[256 + rt]; const size_t off = (size_t)(u.pm * BM + rt) * 1024 + col0;
; #pragma unroll
;                 for (int bj = 0; bj < 2; ++bj) {
;                     const u32x4 xw = *(const u32x4*)(x1b + off + bj * HALF);
;                     f32x4 x0, x1;
;                     x0[0] = __uint_as_float(xw.x << 16); x0[1] = __uint_as_float(xw.x & 0xffff0000u); x0[2] = __uint_as_float(xw.y << 16); x0[3] = __uint_as_float(xw.y & 0xffff0000u);
;                     x1[0] = __uint_as_float(xw.z << 16); x1[1] = __uint_as_float(xw.z & 0xffff0000u); x1[2] = __uint_as_float(xw.w << 16); x1[3] = __uint_as_float(xw.w & 0xffff0000u);
;                     const f32x4 v0 = x0 + acc[ai][bj][m][0] * r, v1 = x1 + acc[ai][bj][m][1] * r;
;                     u32x4 w; w.x = cvt_pk_bf16(v0[0], v0[1]); w.y = cvt_pk_bf16(v0[2], v0[3]); w.z = cvt_pk_bf16(v1[0], v1[1]); w.w = cvt_pk_bf16(v1[2], v1[3]);
;                     *(u32x4*)(x1b + off + bj * HALF) = w; } }
	v_pk_fma_f32 v[58:59], v[70:71], v[72:73], v[58:59] op_sel_hi:[1,0,1]
	v_pk_fma_f32 v[56:57], v[68:69], v[72:73], v[56:57] op_sel_hi:[1,0,1]
	v_pk_fma_f32 v[62:63], v[66:67], v[72:73], v[62:63] op_sel_hi:[1,0,1]
	v_pk_fma_f32 v[60:61], v[64:65], v[72:73], v[60:61] op_sel_hi:[1,0,1]
	v_cvt_pk_bf16_f32 v56, v56, v57
	v_cvt_pk_bf16_f32 v57, v58, v59
	v_add_u32_e32 v64, 0x90, v130
	v_cvt_pk_bf16_f32 v58, v60, v61
	v_cvt_pk_bf16_f32 v59, v62, v63
	s_waitcnt vmcnt(14)
	v_mov_b32_e32 v60, v188
	v_mov_b32_e32 v61, v189
	v_mov_b32_e32 v62, v190
	v_mov_b32_e32 v63, v191
	v_ashrrev_i32_e32 v65, 31, v64
	v_lshlrev_b64 v[64:65], 11, v[64:65]
	v_lshl_add_u64 v[64:65], s[24:25], 0, v[64:65]
	global_store_dwordx4 v[80:81], v[56:59], off
	v_lshl_add_u64 v[64:65], v[64:65], 0, v[128:129]
	s_nop 0
	v_lshlrev_b32_e32 v56, 16, v60
	v_and_b32_e32 v57, 0xffff0000, v60
	v_lshlrev_b32_e32 v58, 16, v61
	v_and_b32_e32 v59, 0xffff0000, v61
	v_lshlrev_b32_e32 v60, 16, v62
	v_and_b32_e32 v61, 0xffff0000, v62
	v_lshlrev_b32_e32 v62, 16, v63
	v_and_b32_e32 v63, 0xffff0000, v63
	v_pk_fma_f32 v[50:51], v[50:51], v[72:73], v[58:59] op_sel_hi:[1,0,1]
	v_pk_fma_f32 v[48:49], v[48:49], v[72:73], v[56:57] op_sel_hi:[1,0,1]
	v_pk_fma_f32 v[54:55], v[54:55], v[72:73], v[62:63] op_sel_hi:[1,0,1]
	v_pk_fma_f32 v[52:53], v[52:53], v[72:73], v[60:61] op_sel_hi:[1,0,1]
	v_cvt_pk_bf16_f32 v48, v48, v49
	v_cvt_pk_bf16_f32 v49, v50, v51
	s_nop 0
	v_cvt_pk_bf16_f32 v50, v52, v53
	v_cvt_pk_bf16_f32 v51, v54, v55
	s_waitcnt vmcnt(14)
	v_mov_b32_e32 v52, v192
	v_mov_b32_e32 v53, v193
	v_mov_b32_e32 v54, v194
	v_mov_b32_e32 v55, v195
	ds_read_b32 v56, v131 offset:1600
	global_store_dwordx4 v[80:81], v[48:51], off offset:256
	s_nop 0
	s_nop 0
	v_lshlrev_b32_e32 v48, 16, v52
	v_and_b32_e32 v49, 0xffff0000, v52
	v_lshlrev_b32_e32 v50, 16, v53
	v_and_b32_e32 v51, 0xffff0000, v53
	v_lshlrev_b32_e32 v52, 16, v54
	v_and_b32_e32 v53, 0xffff0000, v54
	v_lshlrev_b32_e32 v54, 16, v55
	v_and_b32_e32 v55, 0xffff0000, v55
	s_waitcnt lgkmcnt(0)
	v_pk_fma_f32 v[46:47], v[46:47], v[56:57], v[50:51] op_sel_hi:[1,0,1]
	v_pk_fma_f32 v[44:45], v[44:45], v[56:57], v[48:49] op_sel_hi:[1,0,1]
	v_pk_fma_f32 v[48:49], v[42:43], v[56:57], v[54:55] op_sel_hi:[1,0,1]
	v_pk_fma_f32 v[42:43], v[40:41], v[56:57], v[52:53] op_sel_hi:[1,0,1]
	v_cvt_pk_bf16_f32 v40, v44, v45
	v_cvt_pk_bf16_f32 v41, v46, v47
	s_nop 0
	v_cvt_pk_bf16_f32 v42, v42, v43
	v_cvt_pk_bf16_f32 v43, v48, v49
	s_waitcnt vmcnt(14)
	v_mov_b32_e32 v44, v196
	v_mov_b32_e32 v45, v197
	v_mov_b32_e32 v46, v198
	v_mov_b32_e32 v47, v199
	v_add_u32_e32 v48, 0xa0, v130
	v_ashrrev_i32_e32 v49, 31, v48
	v_lshlrev_b64 v[48:49], 11, v[48:49]
	v_lshl_add_u64 v[48:49], s[24:25], 0, v[48:49]
	global_store_dwordx4 v[64:65], v[40:43], off
	v_lshl_add_u64 v[48:49], v[48:49], 0, v[128:129]
	s_nop 0
	v_lshlrev_b32_e32 v40, 16, v44
	v_and_b32_e32 v41, 0xffff0000, v44
	v_lshlrev_b32_e32 v42, 16, v45
	v_and_b32_e32 v43, 0xffff0000, v45
	v_lshlrev_b32_e32 v44, 16, v46
	v_and_b32_e32 v45, 0xffff0000, v46
	v_lshlrev_b32_e32 v46, 16, v47
	v_and_b32_e32 v47, 0xffff0000, v47
	v_pk_fma_f32 v[34:35], v[34:35], v[56:57], v[42:43] op_sel_hi:[1,0,1]
	v_pk_fma_f32 v[32:33], v[32:33], v[56:57], v[40:41] op_sel_hi:[1,0,1]
	v_pk_fma_f32 v[38:39], v[38:39], v[56:57], v[46:47] op_sel_hi:[1,0,1]
	v_pk_fma_f32 v[36:37], v[36:37], v[56:57], v[44:45] op_sel_hi:[1,0,1]
	v_cvt_pk_bf16_f32 v32, v32, v33
	v_cvt_pk_bf16_f32 v33, v34, v35
	s_nop 0
	v_cvt_pk_bf16_f32 v34, v36, v37
	v_cvt_pk_bf16_f32 v35, v38, v39
	s_waitcnt vmcnt(14)
	v_mov_b32_e32 v36, v200
	v_mov_b32_e32 v37, v201
	v_mov_b32_e32 v38, v202
	v_mov_b32_e32 v39, v203
	ds_read_b32 v40, v131 offset:1664
	global_store_dwordx4 v[64:65], v[32:35], off offset:256
	s_nop 0
	s_nop 0
	v_lshlrev_b32_e32 v32, 16, v36
	v_and_b32_e32 v33, 0xffff0000, v36
	v_lshlrev_b32_e32 v34, 16, v37
	v_and_b32_e32 v35, 0xffff0000, v37
	v_lshlrev_b32_e32 v36, 16, v38
	v_and_b32_e32 v37, 0xffff0000, v38
	v_lshlrev_b32_e32 v38, 16, v39
	v_and_b32_e32 v39, 0xffff0000, v39
	s_waitcnt lgkmcnt(0)
; __device__ __forceinline__ unsigned cvt_pk_bf16(float lo, float hi) { unsigned r; asm volatile("v_cvt_pk_bf16_f32 %0, %1, %2" : "=v"(r) : "v"(lo), "v"(hi)); return r; }
; #define PG8_WAIT_V(n) asm volatile("s_waitcnt vmcnt(" #n ")" ::: "memory")
; #define PG8_BAR __builtin_amdgcn_s_barrier()
;     __device__ __forceinline__ void operator()(const f32x4 (&acc)[2][2][4][2], const Unit& u, int wr, int wc, int fr, int fq) const {
;     ...
;             for (int m = 0; m < 4; ++m) { const int rt = ai * HALF + wr * 64 + m * 16 + fr; const float r = tab[256 + rt]; const size_t off = (size_t)(u.pm * BM + rt) * 1024 + col0;
; #pragma unroll
;                 for (int bj = 0; bj < 2; ++bj) {
;                     const u32x4 xw = *(const u32x4*)(x1b + off + bj * HALF);
;                     f32x4 x0, x1;
;                     x0[0] = __uint_as_float(xw.x << 16); x0[1] = __uint_as_float(xw.x & 0xffff0000u); x0[2] = __uint_as_float(xw.y << 16); x0[3] = __uint_as_float(xw.y & 0xffff0000u);
;                     x1[0] = __uint_as_float(xw.z << 16); x1[1] = __uint_as_float(xw.z & 0xffff0000u); x1[2] = __uint_as_float(xw.w << 16); x1[3] = __uint_as_float(xw.w & 0xffff0000u);
;                     const f32x4 v0 = x0 + acc[ai][bj][m][0] * r, v1 = x1 + acc[ai][bj][m][1] * r;
;                     u32x4 w; w.x = cvt_pk_bf16(v0[0], v0[1]); w.y = cvt_pk_bf16(v0[2], v0[3]); w.z = cvt_pk_bf16(v1[0], v1[1]); w.w = cvt_pk_bf16(v1[2], v1[3]);
;                     *(u32x4*)(x1b + off + bj * HALF) = w; } }
; template <int ROT, class Epi0, class Epi1, class Late, class Post0>
; __device__ __forceinline__ void gemm_phase_pair(PG8_LAS unsigned char* lds, const Gemm g0, const Gemm g1, const Unit u, const Epi0& E0, const Epi1& E1, int wid_in, const Late& late, const Post0& post0) {
;     ...
;     E0(acc, u, wr, wc, fr, fq);
;     PG8_WAIT_V(0); PG8_BAR; post0();
	v_pk_fma_f32 v[30:31], v[30:31], v[40:41], v[34:35] op_sel_hi:[1,0,1]
	v_pk_fma_f32 v[28:29], v[28:29], v[40:41], v[32:33] op_sel_hi:[1,0,1]
	v_pk_fma_f32 v[32:33], v[26:27], v[40:41], v[38:39] op_sel_hi:[1,0,1]
	v_pk_fma_f32 v[26:27], v[24:25], v[40:41], v[36:37] op_sel_hi:[1,0,1]
	v_cvt_pk_bf16_f32 v24, v28, v29
	v_cvt_pk_bf16_f32 v25, v30, v31
	s_nop 0
	v_cvt_pk_bf16_f32 v26, v26, v27
	v_cvt_pk_bf16_f32 v27, v32, v33
	s_waitcnt vmcnt(14)
	v_mov_b32_e32 v28, v204
	v_mov_b32_e32 v29, v205
	v_mov_b32_e32 v30, v206
	v_mov_b32_e32 v31, v207
	v_add_u32_e32 v32, 0xb0, v130
	v_ashrrev_i32_e32 v33, 31, v32
	v_lshlrev_b64 v[32:33], 11, v[32:33]
	v_lshl_add_u64 v[32:33], s[24:25], 0, v[32:33]
	global_store_dwordx4 v[48:49], v[24:27], off
	v_lshl_add_u64 v[32:33], v[32:33], 0, v[128:129]
	s_nop 0
	v_lshlrev_b32_e32 v24, 16, v28
	v_and_b32_e32 v25, 0xffff0000, v28
	v_lshlrev_b32_e32 v26, 16, v29
	v_and_b32_e32 v27, 0xffff0000, v29
	v_lshlrev_b32_e32 v28, 16, v30
	v_and_b32_e32 v29, 0xffff0000, v30
	v_lshlrev_b32_e32 v30, 16, v31
	v_and_b32_e32 v31, 0xffff0000, v31
	v_pk_fma_f32 v[18:19], v[18:19], v[40:41], v[26:27] op_sel_hi:[1,0,1]
	v_pk_fma_f32 v[16:17], v[16:17], v[40:41], v[24:25] op_sel_hi:[1,0,1]
	v_pk_fma_f32 v[22:23], v[22:23], v[40:41], v[30:31] op_sel_hi:[1,0,1]
	v_pk_fma_f32 v[20:21], v[20:21], v[40:41], v[28:29] op_sel_hi:[1,0,1]
	v_cvt_pk_bf16_f32 v16, v16, v17
	v_cvt_pk_bf16_f32 v17, v18, v19
	s_nop 0
	v_cvt_pk_bf16_f32 v18, v20, v21
	v_cvt_pk_bf16_f32 v19, v22, v23
	s_waitcnt vmcnt(14)
	v_mov_b32_e32 v20, v208
	v_mov_b32_e32 v21, v209
	v_mov_b32_e32 v22, v210
	v_mov_b32_e32 v23, v211
	ds_read_b32 v24, v131 offset:1728
	global_store_dwordx4 v[48:49], v[16:19], off offset:256
	s_nop 0
	s_nop 0
	v_lshlrev_b32_e32 v16, 16, v20
	v_and_b32_e32 v17, 0xffff0000, v20
	v_lshlrev_b32_e32 v18, 16, v21
	v_and_b32_e32 v19, 0xffff0000, v21
	v_lshlrev_b32_e32 v20, 16, v22
	v_and_b32_e32 v21, 0xffff0000, v22
	v_lshlrev_b32_e32 v22, 16, v23
	v_and_b32_e32 v23, 0xffff0000, v23
	s_waitcnt lgkmcnt(0)
	v_pk_fma_f32 v[14:15], v[14:15], v[24:25], v[18:19] op_sel_hi:[1,0,1]
	v_pk_fma_f32 v[12:13], v[12:13], v[24:25], v[16:17] op_sel_hi:[1,0,1]
	v_pk_fma_f32 v[16:17], v[10:11], v[24:25], v[22:23] op_sel_hi:[1,0,1]
	v_pk_fma_f32 v[10:11], v[8:9], v[24:25], v[20:21] op_sel_hi:[1,0,1]
	v_cvt_pk_bf16_f32 v8, v12, v13
	v_cvt_pk_bf16_f32 v9, v14, v15
	s_nop 0
	v_cvt_pk_bf16_f32 v10, v10, v11
	v_cvt_pk_bf16_f32 v11, v16, v17
	s_waitcnt vmcnt(14)
	v_mov_b32_e32 v12, v212
	v_mov_b32_e32 v13, v213
	v_mov_b32_e32 v14, v214
	v_mov_b32_e32 v15, v215
	s_nop 0
	global_store_dwordx4 v[32:33], v[8:11], off
	s_nop 0
	s_nop 0
	v_lshlrev_b32_e32 v8, 16, v12
	v_and_b32_e32 v9, 0xffff0000, v12
	v_lshlrev_b32_e32 v10, 16, v13
	v_and_b32_e32 v11, 0xffff0000, v13
	v_lshlrev_b32_e32 v12, 16, v14
	v_and_b32_e32 v13, 0xffff0000, v14
	v_lshlrev_b32_e32 v14, 16, v15
	v_and_b32_e32 v15, 0xffff0000, v15
	v_pk_fma_f32 v[4:5], v[4:5], v[24:25], v[8:9] op_sel_hi:[1,0,1]
	v_pk_fma_f32 v[8:9], v[2:3], v[24:25], v[14:15] op_sel_hi:[1,0,1]
	v_pk_fma_f32 v[2:3], v[0:1], v[24:25], v[12:13] op_sel_hi:[1,0,1]
	v_pk_fma_f32 v[6:7], v[6:7], v[24:25], v[10:11] op_sel_hi:[1,0,1]
	v_cvt_pk_bf16_f32 v0, v4, v5
	s_nop 0
	v_cvt_pk_bf16_f32 v1, v6, v7
	v_cvt_pk_bf16_f32 v2, v2, v3
	v_cvt_pk_bf16_f32 v3, v8, v9
	global_store_dwordx4 v[32:33], v[0:3], off offset:256
	s_waitcnt vmcnt(0)
	s_barrier
	s_cbranch_vccnz .LBB0_884
	v_mbcnt_lo_u32_b32 v0, -1, 0
	v_mbcnt_hi_u32_b32 v0, -1, v0
	s_nop 0
	v_cmp_eq_u32_e32 vcc, 0, v0
	s_and_saveexec_b64 s[8:9], vcc
	s_cbranch_execz .LBB0_883
	s_mov_b64 s[24:25], exec
	v_mbcnt_lo_u32_b32 v0, s24, 0
	v_mbcnt_hi_u32_b32 v0, s25, v0
	v_cmp_eq_u32_e32 vcc, 0, v0
	s_and_b64 s[26:27], exec, vcc
	s_mov_b64 exec, s[26:27]
	s_cbranch_execz .LBB0_883
	s_bcnt1_i32_b64 s7, s[24:25]
	v_mov_b32_e32 v0, 0
	v_mov_b32_e32 v1, s7
	global_atomic_add v0, v1, s[10:11]
